# grid barrier L2 write-back only after the GQA/SWA in-proj phases; MLA kpe and P0 rope-table stores write-through
# baseline (speedup 1.0000x reference)
.LBB0_60:
	s_andn2_saveexec_b64 s[2:3], s[10:11]
	s_cbranch_execz .LBB0_80
	s_mov_b64 s[2:3], exec
	s_cmp_eq_u32 s73, 9
	s_cbranch_scc1 .Lbar_wb
	s_cmp_lg_u32 s73, 14
	s_cbranch_scc1 .Lbar_nowb
.Lbar_wb:
	buffer_wbl2 sc1
.Lbar_nowb:
	s_waitcnt lgkmcnt(0)
	s_waitcnt vmcnt(0)
	v_mbcnt_lo_u32_b32 v1, s2, 0
	v_mbcnt_hi_u32_b32 v1, s3, v1
	v_cmp_eq_u32_e32 vcc, 0, v1
	s_and_saveexec_b64 s[10:11], vcc
	s_cbranch_execz .LBB0_63
	s_bcnt1_i32_b64 s2, s[2:3]
	v_mov_b32_e32 v2, s2
	v_mov_b32_e32 v3, 0x7000
	global_atomic_add v2, v3, v2, s[6:7] offset:1024 sc0

.Lm0_P2b:
	v_cmp_eq_u32_e64 s[50:51], 1, v191
	v_cmp_eq_u32_e64 s[58:59], 2, v191
	v_cmp_eq_u32_e64 s[96:97], 3, v191
	v_mul_f32_e32 v136, v127, v127
	v_fmac_f32_e32 v136, v126, v126
	v_fmac_f32_e32 v136, v128, v128
	v_mul_f32_e32 v160, v129, v129
	v_mul_f32_e32 v161, v123, v123
	v_add_f32_e32 v136, v160, v136
	v_fmac_f32_e32 v136, v122, v122
	v_mul_f32_e32 v160, v125, v125
	v_add_f32_e32 v136, v161, v136
	v_fmac_f32_e32 v136, v124, v124
	v_add_f32_e32 v136, v160, v136
	v_mul_f32_e32 v137, v109, v109
	v_fmac_f32_e32 v137, v108, v108
	v_fmac_f32_e32 v137, v110, v110
	v_mul_f32_e32 v160, v111, v111
	v_mul_f32_e32 v161, v105, v105
	v_add_f32_e32 v137, v160, v137
	v_fmac_f32_e32 v137, v104, v104
	v_mul_f32_e32 v160, v107, v107
	v_add_f32_e32 v137, v161, v137
	v_fmac_f32_e32 v137, v106, v106
	v_add_f32_e32 v137, v160, v137
	v_mul_f32_e32 v138, v93, v93
	v_fmac_f32_e32 v138, v92, v92
	v_fmac_f32_e32 v138, v94, v94
	v_mul_f32_e32 v160, v95, v95
	v_mul_f32_e32 v161, v89, v89
	v_add_f32_e32 v138, v160, v138
	v_fmac_f32_e32 v138, v88, v88
	v_mul_f32_e32 v160, v91, v91
	v_add_f32_e32 v138, v161, v138
	v_fmac_f32_e32 v138, v90, v90
	v_add_f32_e32 v138, v160, v138
	v_mul_f32_e32 v139, v77, v77
	v_fmac_f32_e32 v139, v76, v76
	v_fmac_f32_e32 v139, v78, v78
	v_mul_f32_e32 v160, v79, v79
	v_mul_f32_e32 v161, v73, v73
	v_add_f32_e32 v139, v160, v139
	v_fmac_f32_e32 v139, v72, v72
	v_mul_f32_e32 v160, v75, v75
	v_add_f32_e32 v139, v161, v139
	v_fmac_f32_e32 v139, v74, v74
	v_add_f32_e32 v139, v160, v139
	v_mul_f32_e32 v140, v61, v61
	v_fmac_f32_e32 v140, v60, v60
	v_fmac_f32_e32 v140, v62, v62
	v_mul_f32_e32 v160, v63, v63
	v_mul_f32_e32 v161, v57, v57
	v_add_f32_e32 v140, v160, v140
	v_fmac_f32_e32 v140, v56, v56
	v_mul_f32_e32 v160, v59, v59
	v_add_f32_e32 v140, v161, v140
	v_fmac_f32_e32 v140, v58, v58
	v_add_f32_e32 v140, v160, v140
	v_mul_f32_e32 v141, v45, v45
	v_fmac_f32_e32 v141, v44, v44
	v_fmac_f32_e32 v141, v46, v46
	v_mul_f32_e32 v160, v47, v47
	v_mul_f32_e32 v161, v41, v41
	v_add_f32_e32 v141, v160, v141
	v_fmac_f32_e32 v141, v40, v40
	v_mul_f32_e32 v160, v43, v43
	v_add_f32_e32 v141, v161, v141
	v_fmac_f32_e32 v141, v42, v42
	v_add_f32_e32 v141, v160, v141
	v_mul_f32_e32 v142, v29, v29
	v_fmac_f32_e32 v142, v28, v28
	v_fmac_f32_e32 v142, v30, v30
	v_mul_f32_e32 v160, v31, v31
	v_mul_f32_e32 v161, v25, v25
	v_add_f32_e32 v142, v160, v142
	v_fmac_f32_e32 v142, v24, v24
	v_mul_f32_e32 v160, v27, v27
	v_add_f32_e32 v142, v161, v142
	v_fmac_f32_e32 v142, v26, v26
	v_add_f32_e32 v142, v160, v142
	v_mul_f32_e32 v143, v13, v13
	v_fmac_f32_e32 v143, v12, v12
	v_fmac_f32_e32 v143, v14, v14
	v_mul_f32_e32 v160, v15, v15
	v_mul_f32_e32 v161, v5, v5
	v_add_f32_e32 v143, v160, v143
	v_fmac_f32_e32 v143, v4, v4
	v_mul_f32_e32 v160, v7, v7
	v_add_f32_e32 v143, v161, v143
	v_fmac_f32_e32 v143, v6, v6
	v_add_f32_e32 v143, v160, v143
	ds_swizzle_b32 v144, v136 offset:swizzle(SWAP,16)
	ds_swizzle_b32 v145, v137 offset:swizzle(SWAP,16)
	ds_swizzle_b32 v146, v138 offset:swizzle(SWAP,16)
	ds_swizzle_b32 v147, v139 offset:swizzle(SWAP,16)
	ds_swizzle_b32 v148, v140 offset:swizzle(SWAP,16)
	ds_swizzle_b32 v149, v141 offset:swizzle(SWAP,16)
	ds_swizzle_b32 v150, v142 offset:swizzle(SWAP,16)
	ds_swizzle_b32 v151, v143 offset:swizzle(SWAP,16)
	s_waitcnt lgkmcnt(0)
	v_add_f32_e32 v136, v136, v144
	v_add_f32_e32 v137, v137, v145
	v_add_f32_e32 v138, v138, v146
	v_add_f32_e32 v139, v139, v147
	v_add_f32_e32 v140, v140, v148
	v_add_f32_e32 v141, v141, v149
	v_add_f32_e32 v142, v142, v150
	v_add_f32_e32 v143, v143, v151
	v_mov_b32_e32 v144, v136
	v_mov_b32_e32 v145, v137
	v_mov_b32_e32 v146, v138
	v_mov_b32_e32 v147, v139
	v_mov_b32_e32 v148, v140
	v_mov_b32_e32 v149, v141
	v_mov_b32_e32 v150, v142
	v_mov_b32_e32 v151, v143
	s_nop 1
	v_permlane32_swap_b32 v136, v144
	v_permlane32_swap_b32 v137, v145
	v_permlane32_swap_b32 v138, v146
	v_permlane32_swap_b32 v139, v147
	v_permlane32_swap_b32 v140, v148
	v_permlane32_swap_b32 v141, v149
	v_permlane32_swap_b32 v142, v150
	v_permlane32_swap_b32 v143, v151
	s_nop 1
	v_add_f32_e32 v136, v136, v144
	v_add_f32_e32 v137, v137, v145
	v_add_f32_e32 v138, v138, v146
	v_add_f32_e32 v139, v139, v147
	v_add_f32_e32 v140, v140, v148
	v_add_f32_e32 v141, v141, v149
	v_add_f32_e32 v142, v142, v150
	v_add_f32_e32 v143, v143, v151
	v_cvt_pk_bf16_f32 v152, v126, v127
	v_cvt_pk_bf16_f32 v153, v128, v129
	v_cvt_pk_bf16_f32 v154, v122, v123
	v_cvt_pk_bf16_f32 v155, v124, v125
	global_store_dwordx4 v130, v[152:155], s[6:7] sc1
	s_add_u32 s6, s6, s33
	s_addc_u32 s7, s7, 0
	v_cvt_pk_bf16_f32 v156, v118, v119
	v_cvt_pk_bf16_f32 v157, v120, v121
	v_cvt_pk_bf16_f32 v158, v114, v115
	v_cvt_pk_bf16_f32 v159, v116, v117
	global_store_dwordx4 v131, v[156:159], s[48:49] sc1
	s_add_u32 s48, s48, 0x400
	s_addc_u32 s49, s49, 0
	v_cvt_pk_bf16_f32 v152, v108, v109
	v_cvt_pk_bf16_f32 v153, v110, v111
	v_cvt_pk_bf16_f32 v154, v104, v105
	v_cvt_pk_bf16_f32 v155, v106, v107
	global_store_dwordx4 v130, v[152:155], s[6:7] sc1
	s_add_u32 s6, s6, s33
	s_addc_u32 s7, s7, 0
	v_cvt_pk_bf16_f32 v156, v100, v101
	v_cvt_pk_bf16_f32 v157, v102, v103
	v_cvt_pk_bf16_f32 v158, v96, v97
	v_cvt_pk_bf16_f32 v159, v98, v99
	global_store_dwordx4 v131, v[156:159], s[48:49] sc1
	s_add_u32 s48, s48, 0x400
	s_addc_u32 s49, s49, 0
	v_cvt_pk_bf16_f32 v152, v92, v93
	v_cvt_pk_bf16_f32 v153, v94, v95
	v_cvt_pk_bf16_f32 v154, v88, v89
	v_cvt_pk_bf16_f32 v155, v90, v91
	global_store_dwordx4 v130, v[152:155], s[6:7] sc1
	s_add_u32 s6, s6, s33
	s_addc_u32 s7, s7, 0
	v_cvt_pk_bf16_f32 v156, v84, v85
	v_cvt_pk_bf16_f32 v157, v86, v87
	v_cvt_pk_bf16_f32 v158, v80, v81
	v_cvt_pk_bf16_f32 v159, v82, v83
	global_store_dwordx4 v131, v[156:159], s[48:49] sc1
	s_add_u32 s48, s48, 0x400
	s_addc_u32 s49, s49, 0
	v_cvt_pk_bf16_f32 v152, v76, v77
	v_cvt_pk_bf16_f32 v153, v78, v79
	v_cvt_pk_bf16_f32 v154, v72, v73
	v_cvt_pk_bf16_f32 v155, v74, v75
	global_store_dwordx4 v130, v[152:155], s[6:7] sc1
	s_add_u32 s6, s6, s34
	s_addc_u32 s7, s7, 0
	v_cvt_pk_bf16_f32 v156, v68, v69
	v_cvt_pk_bf16_f32 v157, v70, v71
	v_cvt_pk_bf16_f32 v158, v64, v65
	v_cvt_pk_bf16_f32 v159, v66, v67
	global_store_dwordx4 v131, v[156:159], s[48:49] sc1
	s_add_u32 s48, s48, 0x1400
	s_addc_u32 s49, s49, 0
	v_cvt_pk_bf16_f32 v152, v60, v61
	v_cvt_pk_bf16_f32 v153, v62, v63
	v_cvt_pk_bf16_f32 v154, v56, v57
	v_cvt_pk_bf16_f32 v155, v58, v59
	global_store_dwordx4 v130, v[152:155], s[6:7] sc1
	s_add_u32 s6, s6, s33
	s_addc_u32 s7, s7, 0
	v_cvt_pk_bf16_f32 v156, v52, v53
	v_cvt_pk_bf16_f32 v157, v54, v55
	v_cvt_pk_bf16_f32 v158, v48, v49
	v_cvt_pk_bf16_f32 v159, v50, v51
	global_store_dwordx4 v131, v[156:159], s[48:49] sc1
	s_add_u32 s48, s48, 0x400
	s_addc_u32 s49, s49, 0
	v_cvt_pk_bf16_f32 v152, v44, v45
	v_cvt_pk_bf16_f32 v153, v46, v47
	v_cvt_pk_bf16_f32 v154, v40, v41
	v_cvt_pk_bf16_f32 v155, v42, v43
	global_store_dwordx4 v130, v[152:155], s[6:7] sc1
	s_add_u32 s6, s6, s33
	s_addc_u32 s7, s7, 0
	v_cvt_pk_bf16_f32 v156, v36, v37
	v_cvt_pk_bf16_f32 v157, v38, v39
	v_cvt_pk_bf16_f32 v158, v32, v33
	v_cvt_pk_bf16_f32 v159, v34, v35
	global_store_dwordx4 v131, v[156:159], s[48:49] sc1
	s_add_u32 s48, s48, 0x400
	s_addc_u32 s49, s49, 0
	v_cvt_pk_bf16_f32 v152, v28, v29
	v_cvt_pk_bf16_f32 v153, v30, v31
	v_cvt_pk_bf16_f32 v154, v24, v25
	v_cvt_pk_bf16_f32 v155, v26, v27
	global_store_dwordx4 v130, v[152:155], s[6:7] sc1
	s_add_u32 s6, s6, s33
	s_addc_u32 s7, s7, 0
	v_cvt_pk_bf16_f32 v156, v20, v21
	v_cvt_pk_bf16_f32 v157, v22, v23
	v_cvt_pk_bf16_f32 v158, v16, v17
	v_cvt_pk_bf16_f32 v159, v18, v19
	global_store_dwordx4 v131, v[156:159], s[48:49] sc1
	s_add_u32 s48, s48, 0x400
	s_addc_u32 s49, s49, 0
	v_cvt_pk_bf16_f32 v152, v12, v13
	v_cvt_pk_bf16_f32 v153, v14, v15
	v_cvt_pk_bf16_f32 v154, v4, v5
	v_cvt_pk_bf16_f32 v155, v6, v7
	global_store_dwordx4 v130, v[152:155], s[6:7] sc1
	v_cvt_pk_bf16_f32 v156, v8, v9
	v_cvt_pk_bf16_f32 v157, v10, v11
	v_cvt_pk_bf16_f32 v158, v0, v1
	v_cvt_pk_bf16_f32 v159, v2, v3
	global_store_dwordx4 v131, v[156:159], s[48:49] sc1
	v_cndmask_b32_e64 v160, v136, v137, s[50:51]
	v_cndmask_b32_e64 v160, v160, v138, s[58:59]
	v_cndmask_b32_e64 v160, v160, v139, s[96:97]
	v_cndmask_b32_e64 v161, v140, v141, s[50:51]
	v_cndmask_b32_e64 v161, v161, v142, s[58:59]
	v_cndmask_b32_e64 v161, v161, v143, s[96:97]
	global_store_dword v134, v160, s[24:25] sc1
	s_add_u32 s24, s24, s35
	s_addc_u32 s25, s25, 0
	global_store_dword v134, v161, s[24:25] sc1
	s_branch .LBB0_872
.Lm0_P2c:
	global_load_dwordx4 v[164:167], v132, s[8:9]
	global_load_dwordx4 v[168:171], v133, s[8:9]
	v_cmp_eq_u32_e64 s[50:51], 1, v191
	v_cmp_eq_u32_e64 s[58:59], 2, v191
	v_cmp_eq_u32_e64 s[96:97], 3, v191
	v_mul_f32_e32 v136, v127, v127
	v_fmac_f32_e32 v136, v126, v126
	v_fmac_f32_e32 v136, v128, v128
	v_mul_f32_e32 v160, v129, v129
	v_mul_f32_e32 v161, v123, v123
	v_add_f32_e32 v136, v160, v136
	v_fmac_f32_e32 v136, v122, v122
	v_mul_f32_e32 v160, v125, v125
	v_add_f32_e32 v136, v161, v136
	v_fmac_f32_e32 v136, v124, v124
	v_add_f32_e32 v136, v160, v136
	v_mul_f32_e32 v137, v109, v109
	v_fmac_f32_e32 v137, v108, v108
	v_fmac_f32_e32 v137, v110, v110
	v_mul_f32_e32 v160, v111, v111
	v_mul_f32_e32 v161, v105, v105
	v_add_f32_e32 v137, v160, v137
	v_fmac_f32_e32 v137, v104, v104
	v_mul_f32_e32 v160, v107, v107
	v_add_f32_e32 v137, v161, v137
	v_fmac_f32_e32 v137, v106, v106
	v_add_f32_e32 v137, v160, v137
	v_mul_f32_e32 v138, v93, v93
	v_fmac_f32_e32 v138, v92, v92
	v_fmac_f32_e32 v138, v94, v94
	v_mul_f32_e32 v160, v95, v95
	v_mul_f32_e32 v161, v89, v89
	v_add_f32_e32 v138, v160, v138
	v_fmac_f32_e32 v138, v88, v88
	v_mul_f32_e32 v160, v91, v91
	v_add_f32_e32 v138, v161, v138
	v_fmac_f32_e32 v138, v90, v90
	v_add_f32_e32 v138, v160, v138
	v_mul_f32_e32 v139, v77, v77
	v_fmac_f32_e32 v139, v76, v76
	v_fmac_f32_e32 v139, v78, v78
	v_mul_f32_e32 v160, v79, v79
	v_mul_f32_e32 v161, v73, v73
	v_add_f32_e32 v139, v160, v139
	v_fmac_f32_e32 v139, v72, v72
	v_mul_f32_e32 v160, v75, v75
	v_add_f32_e32 v139, v161, v139
	v_fmac_f32_e32 v139, v74, v74
	v_add_f32_e32 v139, v160, v139
	v_mul_f32_e32 v140, v61, v61
	v_fmac_f32_e32 v140, v60, v60
	v_fmac_f32_e32 v140, v62, v62
	v_mul_f32_e32 v160, v63, v63
	v_mul_f32_e32 v161, v57, v57
	v_add_f32_e32 v140, v160, v140
	v_fmac_f32_e32 v140, v56, v56
	v_mul_f32_e32 v160, v59, v59
	v_add_f32_e32 v140, v161, v140
	v_fmac_f32_e32 v140, v58, v58
	v_add_f32_e32 v140, v160, v140
	v_mul_f32_e32 v141, v45, v45
	v_fmac_f32_e32 v141, v44, v44
	v_fmac_f32_e32 v141, v46, v46
	v_mul_f32_e32 v160, v47, v47
	v_mul_f32_e32 v161, v41, v41
	v_add_f32_e32 v141, v160, v141
	v_fmac_f32_e32 v141, v40, v40
	v_mul_f32_e32 v160, v43, v43
	v_add_f32_e32 v141, v161, v141
	v_fmac_f32_e32 v141, v42, v42
	v_add_f32_e32 v141, v160, v141
	v_mul_f32_e32 v142, v29, v29
	v_fmac_f32_e32 v142, v28, v28
	v_fmac_f32_e32 v142, v30, v30
	v_mul_f32_e32 v160, v31, v31
	v_mul_f32_e32 v161, v25, v25
	v_add_f32_e32 v142, v160, v142
	v_fmac_f32_e32 v142, v24, v24
	v_mul_f32_e32 v160, v27, v27
	v_add_f32_e32 v142, v161, v142
	v_fmac_f32_e32 v142, v26, v26
	v_add_f32_e32 v142, v160, v142
	v_mul_f32_e32 v143, v13, v13
	v_fmac_f32_e32 v143, v12, v12
	v_fmac_f32_e32 v143, v14, v14
	v_mul_f32_e32 v160, v15, v15
	v_mul_f32_e32 v161, v5, v5
	v_add_f32_e32 v143, v160, v143
	v_fmac_f32_e32 v143, v4, v4
	v_mul_f32_e32 v160, v7, v7
	v_add_f32_e32 v143, v161, v143
	v_fmac_f32_e32 v143, v6, v6
	v_add_f32_e32 v143, v160, v143
	ds_swizzle_b32 v144, v136 offset:swizzle(SWAP,16)
	ds_swizzle_b32 v145, v137 offset:swizzle(SWAP,16)
	ds_swizzle_b32 v146, v138 offset:swizzle(SWAP,16)
	ds_swizzle_b32 v147, v139 offset:swizzle(SWAP,16)
	ds_swizzle_b32 v148, v140 offset:swizzle(SWAP,16)
	ds_swizzle_b32 v149, v141 offset:swizzle(SWAP,16)
	ds_swizzle_b32 v150, v142 offset:swizzle(SWAP,16)
	ds_swizzle_b32 v151, v143 offset:swizzle(SWAP,16)
	s_waitcnt lgkmcnt(0)
	v_add_f32_e32 v136, v136, v144
	v_add_f32_e32 v137, v137, v145
	v_add_f32_e32 v138, v138, v146
	v_add_f32_e32 v139, v139, v147
	v_add_f32_e32 v140, v140, v148
	v_add_f32_e32 v141, v141, v149
	v_add_f32_e32 v142, v142, v150
	v_add_f32_e32 v143, v143, v151
	v_mov_b32_e32 v144, v136
	v_mov_b32_e32 v145, v137
	v_mov_b32_e32 v146, v138
	v_mov_b32_e32 v147, v139
	v_mov_b32_e32 v148, v140
	v_mov_b32_e32 v149, v141
	v_mov_b32_e32 v150, v142
	v_mov_b32_e32 v151, v143
	s_nop 1
	v_permlane32_swap_b32 v136, v144
	v_permlane32_swap_b32 v137, v145
	v_permlane32_swap_b32 v138, v146
	v_permlane32_swap_b32 v139, v147
	v_permlane32_swap_b32 v140, v148
	v_permlane32_swap_b32 v141, v149
	v_permlane32_swap_b32 v142, v150
	v_permlane32_swap_b32 v143, v151
	s_nop 1
	v_add_f32_e32 v136, v136, v144
	v_add_f32_e32 v137, v137, v145
	v_add_f32_e32 v138, v138, v146
	v_add_f32_e32 v139, v139, v147
	v_add_f32_e32 v140, v140, v148
	v_add_f32_e32 v141, v141, v149
	v_add_f32_e32 v142, v142, v150
	v_add_f32_e32 v143, v143, v151
	s_add_u32 s8, s8, 0x400
	s_addc_u32 s9, s9, 0
	global_load_dwordx4 v[172:175], v132, s[8:9]
	global_load_dwordx4 v[176:179], v133, s[8:9]
	v_cvt_pk_bf16_f32 v152, v126, v127
	v_cvt_pk_bf16_f32 v153, v128, v129
	v_cvt_pk_bf16_f32 v154, v122, v123
	v_cvt_pk_bf16_f32 v155, v124, v125
	global_store_dwordx4 v130, v[152:155], s[6:7] sc1
	s_add_u32 s6, s6, s33
	s_addc_u32 s7, s7, 0
	s_waitcnt vmcnt(3)
	v_pk_mul_f32 v[162:163], v[118:119], v[168:169] op_sel:[1,0] op_sel_hi:[0,0]
	v_pk_fma_f32 v[118:119], v[118:119], v[164:165], v[162:163] op_sel:[0,0,0] op_sel_hi:[1,0,1] neg_lo:[0,0,1]
	v_pk_mul_f32 v[162:163], v[120:121], v[168:169] op_sel:[1,1] op_sel_hi:[0,1]
	v_pk_fma_f32 v[120:121], v[120:121], v[164:165], v[162:163] op_sel:[0,1,0] op_sel_hi:[1,1,1] neg_lo:[0,0,1]
	v_pk_mul_f32 v[162:163], v[114:115], v[170:171] op_sel:[1,0] op_sel_hi:[0,0]
	v_pk_fma_f32 v[114:115], v[114:115], v[166:167], v[162:163] op_sel:[0,0,0] op_sel_hi:[1,0,1] neg_lo:[0,0,1]
	v_pk_mul_f32 v[162:163], v[116:117], v[170:171] op_sel:[1,1] op_sel_hi:[0,1]
	v_pk_fma_f32 v[116:117], v[116:117], v[166:167], v[162:163] op_sel:[0,1,0] op_sel_hi:[1,1,1] neg_lo:[0,0,1]
	v_cvt_pk_bf16_f32 v156, v118, v119
	v_cvt_pk_bf16_f32 v157, v120, v121
	v_cvt_pk_bf16_f32 v158, v114, v115
	v_cvt_pk_bf16_f32 v159, v116, v117
	global_store_dwordx4 v131, v[156:159], s[48:49] sc1
	s_add_u32 s48, s48, 0x400
	s_addc_u32 s49, s49, 0
	s_add_u32 s8, s8, 0x400
	s_addc_u32 s9, s9, 0
	global_load_dwordx4 v[164:167], v132, s[8:9]
	global_load_dwordx4 v[168:171], v133, s[8:9]
	v_cvt_pk_bf16_f32 v152, v108, v109
	v_cvt_pk_bf16_f32 v153, v110, v111
	v_cvt_pk_bf16_f32 v154, v104, v105
	v_cvt_pk_bf16_f32 v155, v106, v107
	global_store_dwordx4 v130, v[152:155], s[6:7] sc1
	s_add_u32 s6, s6, s33
	s_addc_u32 s7, s7, 0
	s_waitcnt vmcnt(5)
	v_pk_mul_f32 v[162:163], v[100:101], v[176:177] op_sel:[1,0] op_sel_hi:[0,0]
	v_pk_fma_f32 v[100:101], v[100:101], v[172:173], v[162:163] op_sel:[0,0,0] op_sel_hi:[1,0,1] neg_lo:[0,0,1]
	v_pk_mul_f32 v[162:163], v[102:103], v[176:177] op_sel:[1,1] op_sel_hi:[0,1]
	v_pk_fma_f32 v[102:103], v[102:103], v[172:173], v[162:163] op_sel:[0,1,0] op_sel_hi:[1,1,1] neg_lo:[0,0,1]
	v_pk_mul_f32 v[162:163], v[96:97], v[178:179] op_sel:[1,0] op_sel_hi:[0,0]
	v_pk_fma_f32 v[96:97], v[96:97], v[174:175], v[162:163] op_sel:[0,0,0] op_sel_hi:[1,0,1] neg_lo:[0,0,1]
	v_pk_mul_f32 v[162:163], v[98:99], v[178:179] op_sel:[1,1] op_sel_hi:[0,1]
	v_pk_fma_f32 v[98:99], v[98:99], v[174:175], v[162:163] op_sel:[0,1,0] op_sel_hi:[1,1,1] neg_lo:[0,0,1]
	v_cvt_pk_bf16_f32 v156, v100, v101
	v_cvt_pk_bf16_f32 v157, v102, v103
	v_cvt_pk_bf16_f32 v158, v96, v97
	v_cvt_pk_bf16_f32 v159, v98, v99
	global_store_dwordx4 v131, v[156:159], s[48:49] sc1
	s_add_u32 s48, s48, 0x400
	s_addc_u32 s49, s49, 0
	s_add_u32 s8, s8, 0x400
	s_addc_u32 s9, s9, 0
	global_load_dwordx4 v[172:175], v132, s[8:9]
	global_load_dwordx4 v[176:179], v133, s[8:9]
	v_cvt_pk_bf16_f32 v152, v92, v93
	v_cvt_pk_bf16_f32 v153, v94, v95
	v_cvt_pk_bf16_f32 v154, v88, v89
	v_cvt_pk_bf16_f32 v155, v90, v91
	global_store_dwordx4 v130, v[152:155], s[6:7] sc1
	s_add_u32 s6, s6, s33
	s_addc_u32 s7, s7, 0
	s_waitcnt vmcnt(5)
	v_pk_mul_f32 v[162:163], v[84:85], v[168:169] op_sel:[1,0] op_sel_hi:[0,0]
	v_pk_fma_f32 v[84:85], v[84:85], v[164:165], v[162:163] op_sel:[0,0,0] op_sel_hi:[1,0,1] neg_lo:[0,0,1]
	v_pk_mul_f32 v[162:163], v[86:87], v[168:169] op_sel:[1,1] op_sel_hi:[0,1]
	v_pk_fma_f32 v[86:87], v[86:87], v[164:165], v[162:163] op_sel:[0,1,0] op_sel_hi:[1,1,1] neg_lo:[0,0,1]
	v_pk_mul_f32 v[162:163], v[80:81], v[170:171] op_sel:[1,0] op_sel_hi:[0,0]
	v_pk_fma_f32 v[80:81], v[80:81], v[166:167], v[162:163] op_sel:[0,0,0] op_sel_hi:[1,0,1] neg_lo:[0,0,1]
	v_pk_mul_f32 v[162:163], v[82:83], v[170:171] op_sel:[1,1] op_sel_hi:[0,1]
	v_pk_fma_f32 v[82:83], v[82:83], v[166:167], v[162:163] op_sel:[0,1,0] op_sel_hi:[1,1,1] neg_lo:[0,0,1]
	v_cvt_pk_bf16_f32 v156, v84, v85
	v_cvt_pk_bf16_f32 v157, v86, v87
	v_cvt_pk_bf16_f32 v158, v80, v81
	v_cvt_pk_bf16_f32 v159, v82, v83
	global_store_dwordx4 v131, v[156:159], s[48:49] sc1
	s_add_u32 s48, s48, 0x400
	s_addc_u32 s49, s49, 0
	s_add_u32 s8, s8, 0x1400
	s_addc_u32 s9, s9, 0
	global_load_dwordx4 v[164:167], v132, s[8:9]
	global_load_dwordx4 v[168:171], v133, s[8:9]
	v_cvt_pk_bf16_f32 v152, v76, v77
	v_cvt_pk_bf16_f32 v153, v78, v79
	v_cvt_pk_bf16_f32 v154, v72, v73
	v_cvt_pk_bf16_f32 v155, v74, v75
	global_store_dwordx4 v130, v[152:155], s[6:7] sc1
	s_add_u32 s6, s6, s34
	s_addc_u32 s7, s7, 0
	s_waitcnt vmcnt(5)
	v_pk_mul_f32 v[162:163], v[68:69], v[176:177] op_sel:[1,0] op_sel_hi:[0,0]
	v_pk_fma_f32 v[68:69], v[68:69], v[172:173], v[162:163] op_sel:[0,0,0] op_sel_hi:[1,0,1] neg_lo:[0,0,1]
	v_pk_mul_f32 v[162:163], v[70:71], v[176:177] op_sel:[1,1] op_sel_hi:[0,1]
	v_pk_fma_f32 v[70:71], v[70:71], v[172:173], v[162:163] op_sel:[0,1,0] op_sel_hi:[1,1,1] neg_lo:[0,0,1]
	v_pk_mul_f32 v[162:163], v[64:65], v[178:179] op_sel:[1,0] op_sel_hi:[0,0]
	v_pk_fma_f32 v[64:65], v[64:65], v[174:175], v[162:163] op_sel:[0,0,0] op_sel_hi:[1,0,1] neg_lo:[0,0,1]
	v_pk_mul_f32 v[162:163], v[66:67], v[178:179] op_sel:[1,1] op_sel_hi:[0,1]
	v_pk_fma_f32 v[66:67], v[66:67], v[174:175], v[162:163] op_sel:[0,1,0] op_sel_hi:[1,1,1] neg_lo:[0,0,1]
	v_cvt_pk_bf16_f32 v156, v68, v69
	v_cvt_pk_bf16_f32 v157, v70, v71
	v_cvt_pk_bf16_f32 v158, v64, v65
	v_cvt_pk_bf16_f32 v159, v66, v67
	global_store_dwordx4 v131, v[156:159], s[48:49] sc1
	s_add_u32 s48, s48, 0x1400
	s_addc_u32 s49, s49, 0
	s_add_u32 s8, s8, 0x400
	s_addc_u32 s9, s9, 0
	global_load_dwordx4 v[172:175], v132, s[8:9]
	global_load_dwordx4 v[176:179], v133, s[8:9]
	v_cvt_pk_bf16_f32 v152, v60, v61
	v_cvt_pk_bf16_f32 v153, v62, v63
	v_cvt_pk_bf16_f32 v154, v56, v57
	v_cvt_pk_bf16_f32 v155, v58, v59
	global_store_dwordx4 v130, v[152:155], s[6:7] sc1
	s_add_u32 s6, s6, s33
	s_addc_u32 s7, s7, 0
	s_waitcnt vmcnt(5)
	v_pk_mul_f32 v[162:163], v[52:53], v[168:169] op_sel:[1,0] op_sel_hi:[0,0]
	v_pk_fma_f32 v[52:53], v[52:53], v[164:165], v[162:163] op_sel:[0,0,0] op_sel_hi:[1,0,1] neg_lo:[0,0,1]
	v_pk_mul_f32 v[162:163], v[54:55], v[168:169] op_sel:[1,1] op_sel_hi:[0,1]
	v_pk_fma_f32 v[54:55], v[54:55], v[164:165], v[162:163] op_sel:[0,1,0] op_sel_hi:[1,1,1] neg_lo:[0,0,1]
	v_pk_mul_f32 v[162:163], v[48:49], v[170:171] op_sel:[1,0] op_sel_hi:[0,0]
	v_pk_fma_f32 v[48:49], v[48:49], v[166:167], v[162:163] op_sel:[0,0,0] op_sel_hi:[1,0,1] neg_lo:[0,0,1]
	v_pk_mul_f32 v[162:163], v[50:51], v[170:171] op_sel:[1,1] op_sel_hi:[0,1]
	v_pk_fma_f32 v[50:51], v[50:51], v[166:167], v[162:163] op_sel:[0,1,0] op_sel_hi:[1,1,1] neg_lo:[0,0,1]
	v_cvt_pk_bf16_f32 v156, v52, v53
	v_cvt_pk_bf16_f32 v157, v54, v55
	v_cvt_pk_bf16_f32 v158, v48, v49
	v_cvt_pk_bf16_f32 v159, v50, v51
	global_store_dwordx4 v131, v[156:159], s[48:49] sc1
	s_add_u32 s48, s48, 0x400
	s_addc_u32 s49, s49, 0
	s_add_u32 s8, s8, 0x400
	s_addc_u32 s9, s9, 0
	global_load_dwordx4 v[164:167], v132, s[8:9]
	global_load_dwordx4 v[168:171], v133, s[8:9]
	v_cvt_pk_bf16_f32 v152, v44, v45
	v_cvt_pk_bf16_f32 v153, v46, v47
	v_cvt_pk_bf16_f32 v154, v40, v41
	v_cvt_pk_bf16_f32 v155, v42, v43
	global_store_dwordx4 v130, v[152:155], s[6:7] sc1
	s_add_u32 s6, s6, s33
	s_addc_u32 s7, s7, 0
	s_waitcnt vmcnt(5)
	v_pk_mul_f32 v[162:163], v[36:37], v[176:177] op_sel:[1,0] op_sel_hi:[0,0]
	v_pk_fma_f32 v[36:37], v[36:37], v[172:173], v[162:163] op_sel:[0,0,0] op_sel_hi:[1,0,1] neg_lo:[0,0,1]
	v_pk_mul_f32 v[162:163], v[38:39], v[176:177] op_sel:[1,1] op_sel_hi:[0,1]
	v_pk_fma_f32 v[38:39], v[38:39], v[172:173], v[162:163] op_sel:[0,1,0] op_sel_hi:[1,1,1] neg_lo:[0,0,1]
	v_pk_mul_f32 v[162:163], v[32:33], v[178:179] op_sel:[1,0] op_sel_hi:[0,0]
	v_pk_fma_f32 v[32:33], v[32:33], v[174:175], v[162:163] op_sel:[0,0,0] op_sel_hi:[1,0,1] neg_lo:[0,0,1]
	v_pk_mul_f32 v[162:163], v[34:35], v[178:179] op_sel:[1,1] op_sel_hi:[0,1]
	v_pk_fma_f32 v[34:35], v[34:35], v[174:175], v[162:163] op_sel:[0,1,0] op_sel_hi:[1,1,1] neg_lo:[0,0,1]
	v_cvt_pk_bf16_f32 v156, v36, v37
	v_cvt_pk_bf16_f32 v157, v38, v39
	v_cvt_pk_bf16_f32 v158, v32, v33
	v_cvt_pk_bf16_f32 v159, v34, v35
	global_store_dwordx4 v131, v[156:159], s[48:49] sc1
	s_add_u32 s48, s48, 0x400
	s_addc_u32 s49, s49, 0
	s_add_u32 s8, s8, 0x400
	s_addc_u32 s9, s9, 0
	global_load_dwordx4 v[172:175], v132, s[8:9]
	global_load_dwordx4 v[176:179], v133, s[8:9]
	v_cvt_pk_bf16_f32 v152, v28, v29
	v_cvt_pk_bf16_f32 v153, v30, v31
	v_cvt_pk_bf16_f32 v154, v24, v25
	v_cvt_pk_bf16_f32 v155, v26, v27
	global_store_dwordx4 v130, v[152:155], s[6:7] sc1
	s_add_u32 s6, s6, s33
	s_addc_u32 s7, s7, 0
	s_waitcnt vmcnt(5)
	v_pk_mul_f32 v[162:163], v[20:21], v[168:169] op_sel:[1,0] op_sel_hi:[0,0]
	v_pk_fma_f32 v[20:21], v[20:21], v[164:165], v[162:163] op_sel:[0,0,0] op_sel_hi:[1,0,1] neg_lo:[0,0,1]
	v_pk_mul_f32 v[162:163], v[22:23], v[168:169] op_sel:[1,1] op_sel_hi:[0,1]
	v_pk_fma_f32 v[22:23], v[22:23], v[164:165], v[162:163] op_sel:[0,1,0] op_sel_hi:[1,1,1] neg_lo:[0,0,1]
	v_pk_mul_f32 v[162:163], v[16:17], v[170:171] op_sel:[1,0] op_sel_hi:[0,0]
	v_pk_fma_f32 v[16:17], v[16:17], v[166:167], v[162:163] op_sel:[0,0,0] op_sel_hi:[1,0,1] neg_lo:[0,0,1]
	v_pk_mul_f32 v[162:163], v[18:19], v[170:171] op_sel:[1,1] op_sel_hi:[0,1]
	v_pk_fma_f32 v[18:19], v[18:19], v[166:167], v[162:163] op_sel:[0,1,0] op_sel_hi:[1,1,1] neg_lo:[0,0,1]
	v_cvt_pk_bf16_f32 v156, v20, v21
	v_cvt_pk_bf16_f32 v157, v22, v23
	v_cvt_pk_bf16_f32 v158, v16, v17
	v_cvt_pk_bf16_f32 v159, v18, v19
	global_store_dwordx4 v131, v[156:159], s[48:49] sc1
	s_add_u32 s48, s48, 0x400
	s_addc_u32 s49, s49, 0
	v_cvt_pk_bf16_f32 v152, v12, v13
	v_cvt_pk_bf16_f32 v153, v14, v15
	v_cvt_pk_bf16_f32 v154, v4, v5
	v_cvt_pk_bf16_f32 v155, v6, v7
	global_store_dwordx4 v130, v[152:155], s[6:7] sc1
	s_waitcnt vmcnt(3)
	v_pk_mul_f32 v[162:163], v[8:9], v[176:177] op_sel:[1,0] op_sel_hi:[0,0]
	v_pk_fma_f32 v[8:9], v[8:9], v[172:173], v[162:163] op_sel:[0,0,0] op_sel_hi:[1,0,1] neg_lo:[0,0,1]
	v_pk_mul_f32 v[162:163], v[10:11], v[176:177] op_sel:[1,1] op_sel_hi:[0,1]
	v_pk_fma_f32 v[10:11], v[10:11], v[172:173], v[162:163] op_sel:[0,1,0] op_sel_hi:[1,1,1] neg_lo:[0,0,1]
	v_pk_mul_f32 v[162:163], v[0:1], v[178:179] op_sel:[1,0] op_sel_hi:[0,0]
	v_pk_fma_f32 v[0:1], v[0:1], v[174:175], v[162:163] op_sel:[0,0,0] op_sel_hi:[1,0,1] neg_lo:[0,0,1]
	v_pk_mul_f32 v[162:163], v[2:3], v[178:179] op_sel:[1,1] op_sel_hi:[0,1]
	v_pk_fma_f32 v[2:3], v[2:3], v[174:175], v[162:163] op_sel:[0,1,0] op_sel_hi:[1,1,1] neg_lo:[0,0,1]
	v_cvt_pk_bf16_f32 v156, v8, v9
	v_cvt_pk_bf16_f32 v157, v10, v11
	v_cvt_pk_bf16_f32 v158, v0, v1
	v_cvt_pk_bf16_f32 v159, v2, v3
	global_store_dwordx4 v131, v[156:159], s[48:49] sc1
	v_cndmask_b32_e64 v160, v136, v137, s[50:51]
	v_cndmask_b32_e64 v160, v160, v138, s[58:59]
	v_cndmask_b32_e64 v160, v160, v139, s[96:97]
	v_cndmask_b32_e64 v161, v140, v141, s[50:51]
	v_cndmask_b32_e64 v161, v161, v142, s[58:59]
	v_cndmask_b32_e64 v161, v161, v143, s[96:97]
	global_store_dword v134, v160, s[24:25] sc1
	s_add_u32 s24, s24, s35
	s_addc_u32 s25, s25, 0
	global_store_dword v134, v161, s[24:25] sc1
	s_branch .LBB0_872

.LBB0_1629:
	v_ashrrev_i32_e32 v5, 10, v12
	v_cvt_f32_i32_e32 v5, v5
	v_bfe_u32 v7, v12, 4, 6
	v_cvt_f32_ubyte0_e32 v8, v7
	v_and_b32_e32 v6, -16, v12
	v_cndmask_b32_e32 v5, v8, v5, vcc
	v_mul_f32_e32 v5, v4, v5
	v_mul_f32_e32 v8, 0.15915494, v5
	v_rndne_f32_e32 v8, v8
	v_fma_f32 v5, v5, 0.15915494, -v8
	v_cos_f32_e32 v10, v5
	v_add_u32_e32 v12, s2, v12
	v_ashrrev_i32_e32 v7, 31, v6
	v_sin_f32_e32 v5, v5
	v_cmp_lt_i32_e64 s[4:5], s3, v12
	v_lshlrev_b64 v[6:7], 2, v[6:7]
	s_or_b64 s[8:9], s[4:5], s[8:9]
	v_lshl_add_u64 v[8:9], v[0:1], 0, v[6:7]
	v_lshl_add_u64 v[6:7], v[2:3], 0, v[6:7]
	global_store_dword v[8:9], v10, off sc1
	global_store_dword v[6:7], v5, off sc1
	s_andn2_b64 exec, exec, s[8:9]
	s_cbranch_execnz .LBB0_1629
